# adds: SEAM(0) grid barrier replaced by an arrival counter waited just before the first modacc read; w_f fill trips issued together
# speedup vs baseline: 1.0126x; 1.0050x over previous
.LBB0_30:
	s_cmp_gt_i32 s91, 1
	s_cselect_b64 s[4:5], -1, 0
	s_and_b64 s[6:7], s[6:7], s[4:5]
	s_andn2_b64 vcc, exec, s[6:7]
	s_cbranch_vccnz .LBB0_85
	s_waitcnt vmcnt(0) lgkmcnt(0)
	s_barrier
	v_readlane_b32 s6, v255, 2
	v_readlane_b32 s7, v255, 3
	s_mov_b64 s[8:9], exec
	s_and_b64 exec, exec, s[6:7]
	s_cbranch_execz .Lp0_arrived
	v_mov_b32_e32 v0, 0
	v_mov_b32_e32 v1, 1
	global_atomic_add v0, v1, s[88:89] offset:2048
.Lp0_arrived:
	s_mov_b64 exec, s[8:9]
	s_branch .LBB0_85

.LBB0_85:
	s_cmp_lt_i32 s90, 2
	s_mov_b32 s49, s71
	s_mov_b32 s48, s70
	s_mov_b64 s[46:47], s[68:69]
	s_load_dwordx16 s[68:83], s[0:1], 0x40
	s_cselect_b64 s[0:1], -1, 0
	s_add_u32 s12, s88, 0x100000
	s_addc_u32 s13, s89, 0
	s_add_u32 s10, s88, 0x200000
	s_addc_u32 s11, s89, 0
	s_waitcnt lgkmcnt(0)
	s_add_u32 s54, s88, 0xc00000
	s_addc_u32 s55, s89, 0
	s_add_u32 s92, s88, 0xe00000
	s_addc_u32 s93, s89, 0
	s_add_u32 s56, s88, 0x1000000
	s_addc_u32 s57, s89, 0
	s_add_u32 s6, s88, 0x1b00000
	s_addc_u32 s7, s89, 0
	s_add_u32 s94, s88, 0x2200000
	v_writelane_b32 v255, s6, 5
	s_addc_u32 s95, s89, 0
	s_and_b64 s[16:17], s[0:1], s[4:5]
	v_writelane_b32 v255, s7, 6
	s_andn2_b64 vcc, exec, s[16:17]
	s_cbranch_vccnz .LBB0_128
	v_mov_b32_e32 v180, v254
	s_movk_i32 s0, 0x400
	s_nop 0
	v_cmp_gt_i32_e32 vcc, s0, v180
	s_and_saveexec_b64 s[0:1], vcc
	s_cbranch_execz .LBB0_89
	s_movk_i32 s4, 0x5020
	v_mov_b64_e32 v[0:1], s[62:63]
	v_mad_i64_i32 v[0:1], s[4:5], v180, s4, v[0:1]
	s_mov_b64 s[4:5], 0x3000
	v_add_u32_e32 v2, 0xfffffe00, v180
	v_lshl_add_u64 v[0:1], v[0:1], 0, s[4:5]
	v_lshl_add_u32 v3, v180, 2, 0
	s_mov_b64 s[4:5], 0
	s_mov_b64 s[6:7], 0xa04000
	s_movk_i32 s8, 0x1ff
	global_load_dwordx4 v[4:7], v[0:1], off
	global_load_dwordx4 v[8:11], v[0:1], off offset:16
	v_lshl_add_u64 v[12:13], v[0:1], 0, s[6:7]
	global_load_dwordx4 v[14:17], v[12:13], off
	global_load_dwordx4 v[18:21], v[12:13], off offset:16
	s_waitcnt vmcnt(3)
	ds_write2st64_b32 v3, v4, v5 offset1:16
	ds_write2st64_b32 v3, v6, v7 offset0:32 offset1:48
	s_waitcnt vmcnt(2)
	ds_write2st64_b32 v3, v8, v9 offset0:64 offset1:80
	ds_write2st64_b32 v3, v10, v11 offset0:96 offset1:112
	v_add_u32_e32 v3, 0x800, v3
	s_waitcnt vmcnt(1)
	ds_write2st64_b32 v3, v14, v15 offset1:16
	ds_write2st64_b32 v3, v16, v17 offset0:32 offset1:48
	s_waitcnt vmcnt(0)
	ds_write2st64_b32 v3, v18, v19 offset0:64 offset1:80
	ds_write2st64_b32 v3, v20, v21 offset0:96 offset1:112
.LBB0_89:
	s_or_b64 exec, exec, s[0:1]
	s_lshl_b32 s0, s3, 3
	s_add_i32 s3, s0, s49
	v_and_b32_e32 v181, 63, v180
	v_readlane_b32 s98, v255, 2
	v_readlane_b32 s99, v255, 3
	s_mov_b64 s[100:101], exec
	s_and_b64 exec, exec, s[98:99]
	s_cbranch_execz .Lp1_wait_done
	v_mov_b32_e32 v218, 0
.Lp1_spin:
	global_load_dword v217, v218, s[88:89] offset:2048 sc1
	s_waitcnt vmcnt(0)
	v_readfirstlane_b32 s98, v217
	s_cmp_ge_u32 s98, s33
	s_cbranch_scc1 .Lp1_acq
	s_sleep 2
	s_branch .Lp1_spin
.Lp1_acq:
	buffer_inv sc1
	s_waitcnt vmcnt(0)
.Lp1_wait_done:
	s_mov_b64 exec, s[100:101]
	s_cmpk_gt_i32 s3, 0x7ff
	s_waitcnt lgkmcnt(0)
	s_barrier
	s_cbranch_scc1 .LBB0_108
	v_mbcnt_lo_u32_b32 v1, -1, 0
	v_mbcnt_hi_u32_b32 v1, -1, v1
	v_mov_b32_e32 v3, 0
	v_and_b32_e32 v4, 64, v1
	v_add_u32_e32 v7, 64, v4
	v_lshlrev_b32_e32 v4, 3, v181
	v_mov_b32_e32 v5, v3
	v_lshl_add_u64 v[130:131], s[94:95], 0, v[4:5]
	v_and_b32_e32 v4, 1, v180
	v_cmp_eq_u32_e32 vcc, 0, v4
	v_and_b32_e32 v4, 2, v180
	v_cmp_eq_u32_e64 s[4:5], 0, v4
	v_and_b32_e32 v4, 4, v180
	v_cmp_eq_u32_e64 s[6:7], 0, v4
	v_and_b32_e32 v4, 3, v180
	v_bfrev_b32_e32 v4, v4
	v_lshrrev_b32_e32 v4, 29, v4
	v_lshrrev_b32_e32 v5, 2, v181
	s_lshl_b32 s18, s3, 3
	v_or_b32_e32 v183, v5, v4
	v_lshlrev_b32_e32 v0, 2, v181
	s_add_u32 s0, s58, 0x1000
	v_lshlrev_b32_e32 v4, 2, v183
	v_mov_b32_e32 v5, v3
	s_addc_u32 s1, s59, 0
	v_lshlrev_b32_e32 v2, 4, v181
	v_lshl_add_u64 v[132:133], s[64:65], 0, v[4:5]
	v_or_b32_e32 v4, 0x100, v0
	v_lshl_add_u64 v[128:129], s[52:53], 0, v[2:3]
	v_add_u32_e32 v182, 0, v2
	v_lshl_add_u64 v[134:135], s[60:61], 0, v[2:3]
	v_lshl_add_u64 v[136:137], s[0:1], 0, v[2:3]
	v_lshl_add_u64 v[138:139], s[58:59], 0, v[2:3]
	v_lshlrev_b32_e32 v2, 2, v4
	v_or_b32_e32 v6, 0x200, v0
	v_lshl_add_u64 v[140:141], s[0:1], 0, v[2:3]
	v_lshlrev_b32_e32 v2, 2, v6
	v_or_b32_e32 v8, 0x300, v0
	v_lshl_add_u64 v[142:143], s[0:1], 0, v[2:3]
	v_lshlrev_b32_e32 v2, 2, v8
	v_lshl_add_u64 v[144:145], s[0:1], 0, v[2:3]
	v_xor_b32_e32 v2, 1, v1
	v_cmp_lt_i32_e64 s[0:1], v2, v7
	v_cmp_gt_u32_e64 s[8:9], 8, v181
	s_lshl_b32 s40, s33, 6
	v_cndmask_b32_e64 v2, v1, v2, s[0:1]
	v_lshlrev_b32_e32 v184, 2, v2
	v_xor_b32_e32 v2, 2, v1
	v_cmp_lt_i32_e64 s[0:1], v2, v7
	v_lshlrev_b32_e32 v190, 2, v0
	v_lshlrev_b32_e32 v191, 2, v4
	v_cndmask_b32_e64 v2, v1, v2, s[0:1]
	v_lshlrev_b32_e32 v185, 2, v2
	v_xor_b32_e32 v2, 4, v1
	v_cmp_lt_i32_e64 s[0:1], v2, v7
	v_lshlrev_b32_e32 v192, 2, v6
	v_lshlrev_b32_e32 v193, 2, v8
	v_cndmask_b32_e64 v2, v1, v2, s[0:1]
	v_lshlrev_b32_e32 v186, 2, v2
	v_xor_b32_e32 v2, 8, v1
	v_cmp_lt_i32_e64 s[0:1], v2, v7
	v_mov_b32_e32 v194, 0x358637bd
	s_mov_b32 s41, 0xbfb8aa3b
	v_cndmask_b32_e64 v2, v1, v2, s[0:1]
	v_lshlrev_b32_e32 v187, 2, v2
	v_xor_b32_e32 v2, 16, v1
	v_cmp_lt_i32_e64 s[0:1], v2, v7
	s_mov_b32 s42, 0x3f2aaaab
	v_mov_b32_e32 v195, 0x3ecc95a3
	v_cndmask_b32_e64 v2, v1, v2, s[0:1]
	v_lshlrev_b32_e32 v188, 2, v2
	v_xor_b32_e32 v2, 32, v1
	v_cmp_lt_i32_e64 s[0:1], v2, v7
	s_mov_b32 s43, 0x3f317218
	s_mov_b32 s44, 0x7f800000
	v_cndmask_b32_e64 v1, v1, v2, s[0:1]
	v_lshlrev_b32_e32 v189, 2, v1
	s_mov_b32 s45, 0x33800000
	v_mov_b32_e32 v146, 0x3f317218
	v_mov_b32_e32 v196, 0x7f800000
	v_mov_b32_e32 v197, 0x7fc00000
	v_mov_b32_e32 v198, 0xff800000
	global_load_dword v216, v[132:133], off
	s_branch .LBB0_92

	.amdhsa_kernel _Z10fwd_kernel4Args
		.amdhsa_group_segment_fixed_size 0
		.amdhsa_private_segment_fixed_size 0
		.amdhsa_kernarg_size 416
		.amdhsa_user_sgpr_count 2
		.amdhsa_user_sgpr_dispatch_ptr 0
		.amdhsa_user_sgpr_queue_ptr 0
		.amdhsa_user_sgpr_kernarg_segment_ptr 1
		.amdhsa_user_sgpr_dispatch_id 0
		.amdhsa_user_sgpr_kernarg_preload_length 0
		.amdhsa_user_sgpr_kernarg_preload_offset 0
		.amdhsa_user_sgpr_private_segment_size 0
		.amdhsa_uses_dynamic_stack 0
		.amdhsa_enable_private_segment 0
		.amdhsa_system_sgpr_workgroup_id_x 1
		.amdhsa_system_sgpr_workgroup_id_y 0
		.amdhsa_system_sgpr_workgroup_id_z 0
		.amdhsa_system_sgpr_workgroup_info 0
		.amdhsa_system_vgpr_workitem_id 2
		.amdhsa_next_free_vgpr 256
		.amdhsa_next_free_sgpr 102
		.amdhsa_accum_offset 256
		.amdhsa_reserve_vcc 1
		.amdhsa_float_round_mode_32 0
		.amdhsa_float_round_mode_16_64 0
		.amdhsa_float_denorm_mode_32 3
		.amdhsa_float_denorm_mode_16_64 3
		.amdhsa_dx10_clamp 1
		.amdhsa_ieee_mode 1
		.amdhsa_fp16_overflow 0
		.amdhsa_tg_split 0
		.amdhsa_exception_fp_ieee_invalid_op 0
		.amdhsa_exception_fp_denorm_src 0
		.amdhsa_exception_fp_ieee_div_zero 0
		.amdhsa_exception_fp_ieee_overflow 0
		.amdhsa_exception_fp_ieee_underflow 0
		.amdhsa_exception_fp_ieee_inexact 0
		.amdhsa_exception_int_div_zero 0
	.end_amdhsa_kernel

amdhsa.kernels:
  - .agpr_count:     0
    .args:
      - .offset:         0
        .size:           160
        .value_kind:     by_value
      - .offset:         160
        .size:           4
        .value_kind:     hidden_block_count_x
      - .offset:         164
        .size:           4
        .value_kind:     hidden_block_count_y
      - .offset:         168
        .size:           4
        .value_kind:     hidden_block_count_z
      - .offset:         172
        .size:           2
        .value_kind:     hidden_group_size_x
      - .offset:         174
        .size:           2
        .value_kind:     hidden_group_size_y
      - .offset:         176
        .size:           2
        .value_kind:     hidden_group_size_z
      - .offset:         178
        .size:           2
        .value_kind:     hidden_remainder_x
      - .offset:         180
        .size:           2
        .value_kind:     hidden_remainder_y
      - .offset:         182
        .size:           2
        .value_kind:     hidden_remainder_z
      - .offset:         200
        .size:           8
        .value_kind:     hidden_global_offset_x
      - .offset:         208
        .size:           8
        .value_kind:     hidden_global_offset_y
      - .offset:         216
        .size:           8
        .value_kind:     hidden_global_offset_z
      - .offset:         224
        .size:           2
        .value_kind:     hidden_grid_dims
      - .offset:         248
        .size:           8
        .value_kind:     hidden_multigrid_sync_arg
      - .offset:         280
        .size:           4
        .value_kind:     hidden_dynamic_lds_size
    .group_segment_fixed_size: 0
    .kernarg_segment_align: 8
    .kernarg_segment_size: 416
    .language:       OpenCL C
    .language_version:
      - 2
      - 0
    .max_flat_workgroup_size: 512
    .name:           _Z10fwd_kernel4Args
    .private_segment_fixed_size: 0
    .sgpr_count:     108
    .sgpr_spill_count: 7
    .symbol:         _Z10fwd_kernel4Args.kd
    .uniform_work_group_size: 1
    .uses_dynamic_stack: false
    .vgpr_count:     256
    .vgpr_spill_count: 0
    .wavefront_size: 64
